# S5: wave 0 only scans; its in-projection tile and u-row ring store moved to wave 1
# speedup vs baseline: 1.0052x; 1.0037x over previous
; __device__ __forceinline__ int opaque_tid() { int t = threadIdx.x; asm volatile("" : "+v"(t)); return t; }
; #define BAR_LDS() asm volatile("s_waitcnt lgkmcnt(0)\n\ts_barrier" ::: "memory")
; __device__ __forceinline__ void s5_unit(const Args& A, char* lds, int b, int g) {
;     const int tid = opaque_tid(), lane = tid & 63, wave = __builtin_amdgcn_readfirstlane(tid >> 6); const int fr = lane & 15, fq = lane >> 4, r32 = lane & 31, hi = lane >> 5;
;     const bf16* P1 = (const bf16*)(A.ws + WS_BIG); bf16* YD = (bf16*)A.out;
;     const unsigned char* pg = A.ws + WS_S5P + (size_t)g * S5P_STRIDE; const bf16* BbT = (const bf16*)pg; const bf16* Cm = (const bf16*)(pg + 4096); const float* ari = (const float*)(pg + 8192);
;     const int ttile = wave >> 2, ntile = wave & 3;
;     const bf16x8 bfrag = *(const bf16x8*)(BbT + (ntile * 32 + r32) * 16 + 8 * hi);
;     bf16x8 cfrag[4];
; #pragma unroll
;     for (int ks = 0; ks < 4; ++ks) cfrag[ks] = *(const bf16x8*)(Cm + fr * 128 + ks * 32 + 8 * fq);
;     const float ar = ari[lane], ai = ari[64 + lane]; float sr = 0.f, si = 0.f;
;     const float dskip = A.in[I_ODSKIP][g * 16 + fr];
;     const size_t rb0 = (size_t)b * SEQL; const bf16* pU = P1 + (rb0 + ttile * 32 + r32) * LD1 + C1_U + g * 16 + 8 * hi;
;     bf16x8 un = *(const bf16x8*)pU;
;     BAR_LDS();
.LBB0_1346:
	s_and_b32 s8, s42, 31
	v_mov_b32_e32 v14, v220
	s_lshl_b32 s44, s8, 5
	s_and_b32 s8, s43, 31
	s_ashr_i32 s16, s43, 5
	v_readfirstlane_b32 s20, v14
	s_ashr_i32 s45, s20, 6
	s_cmp_eq_u32 s45, 1
	s_cselect_b32 s98, 1, 0
	s_mul_i32 s17, s8, 0x2200
	v_and_b32_e32 v48, 15, v14
	s_add_u32 s18, s4, s17
	s_addc_u32 s19, s5, 0
	v_lshlrev_b32_e32 v2, 8, v48
	v_mov_b32_e32 v3, v41
	v_and_b32_e32 v45, 31, v14
	v_lshl_add_u64 v[2:3], s[18:19], 0, v[2:3]
	v_and_b32_e32 v4, 48, v14
	v_mov_b32_e32 v5, v41
	v_and_b32_e32 v15, 63, v14
	s_and_b32 s21, s45, 3
	v_lshlrev_b32_e32 v0, 5, v45
	v_lshl_add_u64 v[2:3], v[2:3], 0, v[4:5]
	v_bfe_u32 v46, v14, 5, 1
	v_lshl_or_b32 v40, s21, 10, v0
	v_lshl_add_u64 v[6:7], v[2:3], 0, s[10:11]
	v_add_co_u32_e32 v2, vcc, s26, v2
	v_lshlrev_b32_e32 v8, 2, v15
	v_mov_b32_e32 v9, v41
	v_lshl_add_u64 v[0:1], s[18:19], 0, v[40:41]
	v_lshlrev_b32_e32 v40, 4, v46
	v_addc_co_u32_e32 v3, vcc, 0, v3, vcc
	v_lshl_add_u64 v[10:11], s[18:19], 0, v[8:9]
	s_ashr_i32 s18, s20, 3
	v_lshl_add_u64 v[0:1], v[0:1], 0, v[40:41]
	v_lshl_add_u64 v[12:13], v[10:11], 0, s[12:13]
	v_add_co_u32_e32 v10, vcc, s27, v10
	s_ashr_i32 s17, s16, 31
	s_and_b32 s46, s18, 0xffffffe0
	v_addc_co_u32_e32 v11, vcc, 0, v11, vcc
	flat_load_dwordx4 v[16:19], v[2:3]
	flat_load_dword v44, v[10:11]
	flat_load_dword v47, v[12:13] offset:256
	flat_load_dwordx4 v[20:23], v[0:1]
	s_cmp_eq_u32 s98, 1
	s_cbranch_scc0 .Ls5_nobf0
	global_load_dwordx4 v[116:119], v[0:1], off offset:-1024
.Ls5_nobf0:
	flat_load_dwordx4 v[24:27], v[6:7] offset:64
	flat_load_dwordx4 v[28:31], v[6:7] offset:128
	flat_load_dwordx4 v[32:35], v[6:7] offset:192
	v_lshlrev_b32_e32 v0, 2, v48
	s_lshl_b64 s[22:23], s[16:17], 11
	s_ashr_i32 s16, s46, 31
	v_lshl_or_b32 v0, s8, 6, v0
	v_mov_b32_e32 v1, v41
	s_add_u32 s17, s22, s46
	v_lshl_add_u64 v[0:1], s[34:35], 0, v[0:1]
	v_or_b32_e32 v2, s17, v45
	flat_load_dword v57, v[0:1]
	s_addc_u32 s19, s23, s16
	v_mad_u64_u32 v[0:1], s[16:17], v2, s29, v[42:43]
	v_mad_i32_i24 v1, s19, v56, v1
	s_lshl_b32 s8, s8, 5
	v_lshl_add_u64 v[0:1], v[0:1], 0, s[8:9]
	v_lshl_add_u64 v[0:1], v[0:1], 0, v[40:41]
	v_add_co_u32_e32 v0, vcc, s30, v0
	s_mulk_i32 s19, 0x3800
	s_nop 0
	v_addc_co_u32_e32 v1, vcc, 0, v1, vcc
	s_waitcnt vmcnt(0) lgkmcnt(0)
	flat_load_dwordx4 v[36:39], v[0:1] offset:3072
	v_mad_u64_u32 v[0:1], s[16:17], v2, s29, 0
	s_lshl_b32 s16, s21, 7
	s_add_i32 s47, s16, 0
	s_cmp_lt_u32 s20, 64
	s_cselect_b64 s[16:17], -1, 0
	s_cmp_gt_i32 s45, 3
	v_add_u32_e32 v1, s19, v1
	v_mov_b32_e32 v2, s18
	s_cselect_b64 s[18:19], -1, 0
	s_add_u32 s24, s1, s8
	s_addc_u32 s25, s0, 0
	s_cmp_eq_u32 s21, 0
	s_cselect_b64 s[20:21], -1, 0
	s_lshl_b32 s8, s45, 4
	v_bfi_b32 v58, s28, v2, v14
	s_sub_i32 s8, s8, 64
	v_lshrrev_b32_e32 v2, 2, v14
	v_and_b32_e32 v3, 12, v2
	v_or_b32_e32 v5, s8, v48
	v_or_b32_e32 v62, s8, v3
	v_mul_lo_u32 v5, v5, s36
	s_add_u32 s8, s22, s8
	s_waitcnt lgkmcnt(0)
	s_barrier
	v_lshl_or_b32 v7, v46, 2, s46
	v_lshlrev_b32_e32 v2, 1, v48
	v_add3_u32 v64, s33, v5, v4
	s_addc_u32 s22, s23, 0
	v_or_b32_e32 v4, s8, v3
	v_mov_b32_e32 v3, v41
	v_lshlrev_b32_e32 v6, 2, v45
	v_add_u32_e32 v63, s31, v2
	v_mov_b32_e32 v5, s22
	v_lshl_add_u64 v[48:49], s[24:25], 0, v[2:3]
	v_mul_lo_u32 v2, v7, s37
	v_or3_b32 v0, v0, s44, v40
	v_add_u32_e32 v59, s31, v40
	v_lshl_add_u32 v60, v15, 3, 0
	v_add_u32_e32 v61, s33, v8
	v_add3_u32 v65, s47, v6, v2
	v_lshlrev_b64 v[50:51], 12, v[4:5]
	v_lshl_add_u64 v[52:53], s[6:7], 0, v[0:1]
	s_movk_i32 s44, 0xff80
	s_mov_b32 s8, -2
	v_mov_b32_e32 v54, 0
	v_mov_b32_e32 v55, v41
	s_waitcnt vmcnt(0) lgkmcnt(0)
	v_mov_b32_e32 v45, v44
	v_xor_b32_e32 v46, 0x80000000, v47
	s_branch .LBB0_1348

; __device__ __forceinline__ void s5_unit(const Args& A, char* lds, int b, int g) {
;     ...
;     for (int i = 0; i < SEQL / 64 + 2; ++i) {
;         if (i < SEQL / 64) { float* BU = (float*)(lds + S5_BU) + (i & 1) * (64 * 132); f32x16 acc = {};
;             acc = __builtin_amdgcn_mfma_f32_32x32x16_bf16(un, bfrag, acc, 0, 0, 0);
;             if (ntile == 0) *(bf16x8*)((bf16*)(lds + S5_US) + ((i & 3) * 64 + ttile * 32 + r32) * 16 + 8 * hi) = un;
;             if (i + 1 < SEQL / 64) un = *(const bf16x8*)(pU + (size_t)(i + 1) * 64 * LD1);
.LBB0_1348:
	s_add_i32 s45, s8, 2
	s_cmp_gt_u32 s45, 31
	s_cbranch_scc1 .LBB0_1353
	s_waitcnt vmcnt(0) lgkmcnt(0)
	s_and_b64 vcc, exec, s[16:17]
	s_cbranch_vccnz .LBB0_1353
	v_mfma_f32_32x32x16_bf16 v[0:15], v[36:39], v[20:23], 0
	s_cmp_eq_u32 s98, 1
	s_cbranch_scc0 .Ls5_noextra_m
	v_mfma_f32_32x32x16_bf16 v[120:135], v[36:39], v[116:119], 0
	s_add_i32 s22, s44, 0x80
	s_and_b32 s22, s22, 0xc0
	v_add_u32_e32 v40, s22, v58
	v_lshl_add_u32 v40, v40, 5, v59
	ds_write_b128 v40, v[36:39]
.Ls5_noextra_m:
	s_andn2_b64 vcc, exec, s[20:21]
	s_cbranch_vccz .LBB0_1362
	s_cmpk_eq_i32 s44, 0x740
	s_cbranch_scc1 .LBB0_1352

; __device__ __forceinline__ void s5_unit(const Args& A, char* lds, int b, int g) {
;     ...
; #pragma unroll
;             for (int r = 0; r < 16; ++r) { const int t = ttile * 32 + (r & 3) + 8 * (r >> 2) + 4 * hi; BU[t * 132 + ntile * 32 + r32] = acc[r]; } }
;         if (wave == 0 && i >= 1 && i <= SEQL / 64) { const float* BU = (const float*)(lds + S5_BU) + ((i - 1) & 1) * (64 * 132); bf16* SS = (bf16*)(lds + S5_SS) + ((i - 1) & 1) * (64 * 136);
.LBB0_1352:
	s_bitcmp1_b32 s45, 0
	s_cselect_b32 s22, 0x8400, 0
	v_add_u32_e32 v40, s22, v65
	s_nop 4
	ds_write2_b32 v40, v0, v1 offset1:132
	v_add_u32_e32 v0, 0x400, v40
	ds_write2_b32 v0, v2, v3 offset0:8 offset1:140
	v_add_u32_e32 v0, 0x1000, v40
	ds_write2_b32 v0, v4, v5 offset0:32 offset1:164
	v_add_u32_e32 v0, 0x1400, v40
	ds_write2_b32 v0, v6, v7 offset0:40 offset1:172
	v_add_u32_e32 v0, 0x2000, v40
	ds_write2_b32 v0, v8, v9 offset0:64 offset1:196
	v_add_u32_e32 v0, 0x2400, v40
	ds_write2_b32 v0, v10, v11 offset0:72 offset1:204
	v_add_u32_e32 v0, 0x3000, v40
	ds_write2_b32 v0, v12, v13 offset0:96 offset1:228
	v_add_u32_e32 v0, 0x3400, v40
	ds_write2_b32 v0, v14, v15 offset0:104 offset1:236
	s_cmp_eq_u32 s98, 1
	s_cbranch_scc0 .Ls5_noextra_w
	s_bitcmp1_b32 s45, 0
	s_cselect_b32 s22, 0x8400, 0
	v_add_u32_e32 v40, s22, v65
	v_subrev_u32_e32 v40, 0x80, v40
	ds_write2_b32 v40, v120, v121 offset1:132
	v_add_u32_e32 v0, 0x400, v40
	ds_write2_b32 v0, v122, v123 offset0:8 offset1:140
	v_add_u32_e32 v0, 0x1000, v40
	ds_write2_b32 v0, v124, v125 offset0:32 offset1:164
	v_add_u32_e32 v0, 0x1400, v40
	ds_write2_b32 v0, v126, v127 offset0:40 offset1:172
	v_add_u32_e32 v0, 0x2000, v40
	ds_write2_b32 v0, v128, v129 offset0:64 offset1:196
	v_add_u32_e32 v0, 0x2400, v40
	ds_write2_b32 v0, v130, v131 offset0:72 offset1:204
	v_add_u32_e32 v0, 0x3000, v40
	ds_write2_b32 v0, v132, v133 offset0:96 offset1:228
	v_add_u32_e32 v0, 0x3400, v40
	ds_write2_b32 v0, v134, v135 offset0:104 offset1:236
.Ls5_noextra_w:
.LBB0_1353:
	s_andn2_b64 vcc, exec, s[16:17]
	s_cbranch_vccnz .LBB0_1360
	s_cmp_lt_i32 s45, 33
	s_cbranch_scc1 .LBB0_1356
	s_cmp_lg_u32 s45, 33
	s_cselect_b64 s[22:23], -1, 0
	s_cbranch_execz .LBB0_1357
	s_branch .LBB0_1358
